# differential loop role B: the four staging stores and the next loads spread one per QK MFMA gap instead of one burst between PV and QK
# speedup vs baseline: 1.0367x; 1.0096x over previous
; template <bool DIFF>
; __device__ __forceinline__ void attn_unit(const AttnP& A, int b, int h, int qi, ldsp lds) {
;     ...
;             QK_BLOCK();
;             s16x4 vlo[8], vhi[8];
; #pragma unroll
;             for (int t = 0; t < 2; ++t)
; #pragma unroll
;                 for (int j = 0; j < 4; ++j) { vlo[t * 4 + j] = vtr(Vb + trb + (16 * j) * VP + t * 64); vhi[t * 4 + j] = vtr(Vb + trb + (16 * j + 8) * VP + t * 64); }
;             __builtin_amdgcn_sched_barrier(0);
;             MASK_BLOCK();
;             bool full = (kt == kt0);
;             float psa, psb;
;             if (!full) {
;                 EXPSUM_BLOCK();
;                 if (__any(psa + psb > 1.0e18f)) { full = true; QK_BLOCK();
;     ...
;             bf16x8 pw[4];
; #pragma unroll
;             for (int j = 0; j < 4; ++j) {
;                 u32x4 pk;
;                 if (j < 2) { const int rb = 8 * (j & 1); pk.x = cvtpk(s0[rb], s0[rb + 1]); pk.y = cvtpk(s0[rb + 2], s0[rb + 3]); pk.z = cvtpk(s0[rb + 4], s0[rb + 5]); pk.w = cvtpk(s0[rb + 6], s0[rb + 7]); }
;                 else { const int rb = 8 * (j & 1); pk.x = cvtpk(s1[rb], s1[rb + 1]); pk.y = cvtpk(s1[rb + 2], s1[rb + 3]); pk.z = cvtpk(s1[rb + 4], s1[rb + 5]); pk.w = cvtpk(s1[rb + 6], s1[rb + 7]); }
;                 pw[j] = __builtin_bit_cast(bf16x8, pk);
;             }
;             __builtin_amdgcn_sched_barrier(0);
;             __builtin_amdgcn_s_setprio(1);
; #pragma unroll
;             for (int t = 0; t < 2; ++t)
; #pragma unroll
;                 for (int j = 0; j < 4; ++j) {
;                     const bf16x8 vf = (bf16x8){vlo[t * 4 + j][0], vlo[t * 4 + j][1], vlo[t * 4 + j][2], vlo[t * 4 + j][3], vhi[t * 4 + j][0], vhi[t * 4 + j][1], vhi[t * 4 + j][2], vhi[t * 4 + j][3]};
;                     o[t] = __builtin_amdgcn_mfma_f32_32x32x16_bf16(vf, pw[j], o[t], 0, 0, 0);
;                 }
;             if (DIFF) {
; #pragma unroll
;                 for (int t = 2; t < NTD; ++t)
; #pragma unroll
;                     for (int j = 0; j < 4; ++j) { vlo[(t - 2) * 4 + j] = vtr(Vb + trb + (16 * j) * VP + t * 64); vhi[(t - 2) * 4 + j] = vtr(Vb + trb + (16 * j + 8) * VP + t * 64); }
;                 __builtin_amdgcn_sched_barrier(0);
; #pragma unroll
;                 for (int t = 2; t < NTD; ++t)
; #pragma unroll
;                     for (int j = 0; j < 4; ++j) {
;                         const int i = (t - 2) * 4 + j;
.Ldb_s_even:
	v_exp_f32_e32 v148, v98
	v_exp_f32_e32 v164, v82
	v_exp_f32_e32 v149, v99
	v_exp_f32_e32 v165, v83
	v_add_f32_e32 v237, 0, v148
	v_add_f32_e32 v238, 0, v164
	v_exp_f32_e32 v150, v100
	v_exp_f32_e32 v166, v84
	v_add_f32_e32 v237, v149, v237
	v_add_f32_e32 v238, v165, v238
	v_exp_f32_e32 v151, v101
	v_exp_f32_e32 v167, v85
	v_add_f32_e32 v237, v150, v237
	v_add_f32_e32 v238, v166, v238
	v_exp_f32_e32 v152, v102
	v_exp_f32_e32 v168, v86
	v_add_f32_e32 v237, v151, v237
	v_add_f32_e32 v238, v167, v238
	v_exp_f32_e32 v153, v103
	v_exp_f32_e32 v169, v87
	v_add_f32_e32 v237, v152, v237
	v_add_f32_e32 v238, v168, v238
	v_exp_f32_e32 v154, v104
	v_exp_f32_e32 v170, v88
	v_add_f32_e32 v237, v153, v237
	v_add_f32_e32 v238, v169, v238
	v_exp_f32_e32 v155, v105
	v_exp_f32_e32 v171, v89
	v_add_f32_e32 v237, v154, v237
	v_add_f32_e32 v238, v170, v238
	v_exp_f32_e32 v156, v106
	v_exp_f32_e32 v172, v90
	v_add_f32_e32 v237, v155, v237
	v_add_f32_e32 v238, v171, v238
	v_exp_f32_e32 v157, v107
	v_exp_f32_e32 v173, v91
	v_add_f32_e32 v237, v156, v237
	v_add_f32_e32 v238, v172, v238
	v_exp_f32_e32 v158, v108
	v_exp_f32_e32 v174, v92
	v_add_f32_e32 v237, v157, v237
	v_add_f32_e32 v238, v173, v238
	v_exp_f32_e32 v159, v109
	v_exp_f32_e32 v175, v93
	v_add_f32_e32 v237, v158, v237
	v_add_f32_e32 v238, v174, v238
	v_exp_f32_e32 v160, v110
	v_exp_f32_e32 v176, v94
	v_add_f32_e32 v237, v159, v237
	v_add_f32_e32 v238, v175, v238
	v_exp_f32_e32 v161, v111
	v_exp_f32_e32 v177, v95
	v_add_f32_e32 v237, v160, v237
	v_add_f32_e32 v238, v176, v238
	v_exp_f32_e32 v162, v112
	v_exp_f32_e32 v178, v96
	v_add_f32_e32 v237, v161, v237
	v_add_f32_e32 v238, v177, v238
	v_exp_f32_e32 v163, v113
	v_exp_f32_e32 v179, v97
	v_add_f32_e32 v237, v162, v237
	v_add_f32_e32 v238, v178, v238
	s_nop 0
	v_add_f32_e32 v237, v163, v237
	v_add_f32_e32 v238, v179, v238
	v_add_f32_e32 v204, v237, v238
	v_cmp_lt_f32_e32 vcc, s85, v204
	s_cbranch_vccnz .Ldb_s_slow
	ds_read_b64_tr_b16 v[90:91], v252 offset:17472
	ds_read_b64_tr_b16 v[92:93], v252 offset:20032
	ds_read_b64_tr_b16 v[94:95], v252 offset:17408
	ds_read_b64_tr_b16 v[96:97], v252 offset:19968
	ds_read_b64_tr_b16 v[106:107], v252 offset:22592
	ds_read_b64_tr_b16 v[108:109], v252 offset:25152
	ds_read_b64_tr_b16 v[110:111], v252 offset:22528
	ds_read_b64_tr_b16 v[112:113], v252 offset:25088
	ds_read_b64_tr_b16 v[240:241], v252 offset:27712
	ds_read_b64_tr_b16 v[242:243], v252 offset:30272
	v_cvt_pk_bf16_f32 v98, v148, v149
	v_cvt_pk_bf16_f32 v99, v150, v151
	v_cvt_pk_bf16_f32 v100, v152, v153
	v_cvt_pk_bf16_f32 v101, v154, v155
	v_cvt_pk_bf16_f32 v102, v156, v157
	v_cvt_pk_bf16_f32 v103, v158, v159
	v_cvt_pk_bf16_f32 v104, v160, v161
	v_cvt_pk_bf16_f32 v105, v162, v163
	v_cvt_pk_bf16_f32 v82, v164, v165
	v_cvt_pk_bf16_f32 v83, v166, v167
	v_cvt_pk_bf16_f32 v84, v168, v169
	v_cvt_pk_bf16_f32 v85, v170, v171
	v_cvt_pk_bf16_f32 v86, v172, v173
	v_cvt_pk_bf16_f32 v87, v174, v175
	v_cvt_pk_bf16_f32 v88, v176, v177
	v_cvt_pk_bf16_f32 v89, v178, v179
	v_add_f32_e32 v230, v204, v230
	ds_read_b64_tr_b16 v[148:149], v252 offset:27648
	ds_read_b64_tr_b16 v[150:151], v252 offset:30208
	ds_read_b64_tr_b16 v[152:153], v252 offset:32768
	ds_read_b64_tr_b16 v[154:155], v252 offset:35328
	ds_read_b64_tr_b16 v[156:157], v252 offset:32832
	ds_read_b64_tr_b16 v[158:159], v252 offset:35392
	s_setprio 1
	s_waitcnt lgkmcnt(14)
	v_mfma_f32_32x32x16_bf16 v[34:49], v[90:93], v[98:101], v[34:49]
	ds_read_b64_tr_b16 v[160:161], v252 offset:17536
	ds_read_b64_tr_b16 v[162:163], v252 offset:20096
	s_waitcnt lgkmcnt(14)
	v_mfma_f32_32x32x16_bf16 v[50:65], v[94:97], v[98:101], v[50:65]
	ds_read_b64_tr_b16 v[164:165], v252 offset:17600
	ds_read_b64_tr_b16 v[166:167], v252 offset:20160
	s_waitcnt lgkmcnt(14)
	v_mfma_f32_32x32x16_bf16 v[34:49], v[106:109], v[102:105], v[34:49]
	ds_read_b64_tr_b16 v[168:169], v252 offset:22656
	ds_read_b64_tr_b16 v[170:171], v252 offset:25216
	s_waitcnt lgkmcnt(14)
	v_mfma_f32_32x32x16_bf16 v[50:65], v[110:113], v[102:105], v[50:65]
	ds_read_b64_tr_b16 v[172:173], v252 offset:22720
	ds_read_b64_tr_b16 v[174:175], v252 offset:25280
	s_waitcnt lgkmcnt(14)
	v_mfma_f32_32x32x16_bf16 v[34:49], v[240:243], v[82:85], v[34:49]
	ds_read_b64_tr_b16 v[176:177], v252 offset:27776
	ds_read_b64_tr_b16 v[178:179], v252 offset:30336
	s_waitcnt lgkmcnt(14)
	v_mfma_f32_32x32x16_bf16 v[50:65], v[148:151], v[82:85], v[50:65]
	ds_read_b64_tr_b16 v[90:91], v252 offset:27840
	ds_read_b64_tr_b16 v[92:93], v252 offset:30400
	s_waitcnt lgkmcnt(14)
	v_mfma_f32_32x32x16_bf16 v[50:65], v[152:155], v[86:89], v[50:65]
	ds_read_b64_tr_b16 v[94:95], v252 offset:32896
	ds_read_b64_tr_b16 v[96:97], v252 offset:35456
	s_waitcnt lgkmcnt(14)
	v_mfma_f32_32x32x16_bf16 v[34:49], v[156:159], v[86:89], v[34:49]
	ds_read_b64_tr_b16 v[106:107], v252 offset:32960
	ds_read_b64_tr_b16 v[108:109], v252 offset:35520
	s_waitcnt lgkmcnt(14)
	v_mfma_f32_32x32x16_bf16 v[18:33], v[160:163], v[98:101], v[18:33]
	ds_read_b128 v[240:243], v234
	s_waitcnt lgkmcnt(13)
	v_mfma_f32_32x32x16_bf16 v[2:17], v[164:167], v[98:101], v[2:17]
	ds_read_b128 v[148:151], v234 offset:8704
	s_waitcnt lgkmcnt(12)
	v_mfma_f32_32x32x16_bf16 v[18:33], v[168:171], v[102:105], v[18:33]
	ds_read_b128 v[152:155], v234 offset:32
	s_waitcnt lgkmcnt(11)
	v_mfma_f32_32x32x16_bf16 v[2:17], v[172:175], v[102:105], v[2:17]
	ds_read_b128 v[156:159], v234 offset:8736
	s_waitcnt lgkmcnt(10)
	v_mfma_f32_32x32x16_bf16 v[18:33], v[176:179], v[82:85], v[18:33]
	ds_read_b128 v[160:163], v234 offset:64
	s_waitcnt lgkmcnt(9)
	v_mfma_f32_32x32x16_bf16 v[2:17], v[90:93], v[82:85], v[2:17]
	ds_read_b128 v[164:167], v234 offset:8768
	s_waitcnt lgkmcnt(8)
; __device__ __forceinline__ s16x4 vtr(ldsp p) { return __builtin_bit_cast(s16x4, __builtin_amdgcn_ds_read_tr16_b64_v4i16((LAS v4i16_t*)p)); }
; #define MASK_BLOCK() do { if (kt == 0 || kt >= diag0) { \
;             _Pragma("unroll") for (int r = 0; r < 16; ++r) { const int kpp = 64 * kt + crow(r, hi); \
;                 if (kpp < 48 || kpp > q_pp) s0[r] = -INFINITY; \
;                 if (kpp + 32 < 48 || kpp + 32 > q_pp) s1[r] = -INFINITY; } } } while (0)
; #define EXPSUM_BLOCK() do { psa = 0.f; psb = 0.f; \
;             _Pragma("unroll") for (int r = 0; r < 16; ++r) { s0[r] = __builtin_amdgcn_exp2f(s0[r]); s1[r] = __builtin_amdgcn_exp2f(s1[r]); psa += s0[r]; asm("" : "+v"(psa)); psb += s1[r]; asm("" : "+v"(psb)); } } while (0)
; template <bool DIFF>
; __device__ __forceinline__ void attn_unit(const AttnP& A, int b, int h, int qi, ldsp lds) {
;     ...
;             QK_BLOCK();
;             s16x4 vlo[8], vhi[8];
; #pragma unroll
;             for (int t = 0; t < 2; ++t)
; #pragma unroll
;                 for (int j = 0; j < 4; ++j) { vlo[t * 4 + j] = vtr(Vb + trb + (16 * j) * VP + t * 64); vhi[t * 4 + j] = vtr(Vb + trb + (16 * j + 8) * VP + t * 64); }
;             __builtin_amdgcn_sched_barrier(0);
;             MASK_BLOCK();
;             bool full = (kt == kt0);
;             float psa, psb;
;             if (!full) {
;                 EXPSUM_BLOCK();
;                 if (__any(psa + psb > 1.0e18f)) { full = true; QK_BLOCK();
	v_mfma_f32_32x32x16_bf16 v[18:33], v[94:97], v[86:89], v[18:33]
	ds_read_b128 v[168:171], v234 offset:96
	s_waitcnt lgkmcnt(7)
	v_mfma_f32_32x32x16_bf16 v[2:17], v[106:109], v[86:89], v[2:17]
	ds_read_b128 v[172:175], v234 offset:8800
	s_waitcnt lgkmcnt(7)
	v_mfma_f32_32x32x16_bf16 v[98:113], v[240:243], v[116:119], v[66:81]
	s_waitcnt vmcnt(0)
	ds_write_b128 v226, v[132:135] offset:38144
	s_waitcnt lgkmcnt(7)
	v_mfma_f32_32x32x16_bf16 v[82:97], v[148:151], v[116:119], v[66:81]
	ds_write_b128 v228, v[140:143] offset:38144
	s_waitcnt lgkmcnt(7)
	v_mfma_f32_32x32x16_bf16 v[98:113], v[152:155], v[120:123], v[98:113]
	ds_write_b128 v227, v[136:139] offset:17408
	s_waitcnt lgkmcnt(7)
	v_mfma_f32_32x32x16_bf16 v[82:97], v[156:159], v[120:123], v[82:97]
	ds_write_b128 v229, v[144:147] offset:17408
	s_waitcnt lgkmcnt(7)
	v_mfma_f32_32x32x16_bf16 v[98:113], v[160:163], v[124:127], v[98:113]
	global_load_dwordx4 v[136:139], v[196:197], off offset:2048
	global_load_dwordx4 v[144:147], v[198:199], off offset:2048
	v_lshl_add_u64 v[196:197], v[196:197], 0, s[26:27]
	s_waitcnt lgkmcnt(6)
	v_mfma_f32_32x32x16_bf16 v[82:97], v[164:167], v[124:127], v[82:97]
	v_lshl_add_u64 v[198:199], v[198:199], 0, s[26:27]
	global_load_dwordx4 v[132:135], v[196:197], off offset:1024
	global_load_dwordx4 v[140:143], v[198:199], off offset:1024
	s_waitcnt lgkmcnt(5)
	v_mfma_f32_32x32x16_bf16 v[98:113], v[168:171], v[128:131], v[98:113]
	s_waitcnt lgkmcnt(4)
	v_mfma_f32_32x32x16_bf16 v[82:97], v[172:175], v[128:131], v[82:97]
	s_setprio 0
	s_waitcnt lgkmcnt(0)
	s_barrier
	s_add_i32 s75, s75, 1
	s_add_i32 s74, s74, 64
	s_cmp_gt_i32 s75, s23
	s_cbranch_scc1 .Ldb_gen
.Ldb_s_odd:
	v_exp_f32_e32 v148, v98
	v_exp_f32_e32 v164, v82
	v_exp_f32_e32 v149, v99
	v_exp_f32_e32 v165, v83
	v_add_f32_e32 v237, 0, v148
	v_add_f32_e32 v238, 0, v164
	v_exp_f32_e32 v150, v100
	v_exp_f32_e32 v166, v84
	v_add_f32_e32 v237, v149, v237
	v_add_f32_e32 v238, v165, v238
	v_exp_f32_e32 v151, v101
	v_exp_f32_e32 v167, v85
	v_add_f32_e32 v237, v150, v237
	v_add_f32_e32 v238, v166, v238
	v_exp_f32_e32 v152, v102
	v_exp_f32_e32 v168, v86
	v_add_f32_e32 v237, v151, v237
	v_add_f32_e32 v238, v167, v238
	v_exp_f32_e32 v153, v103
	v_exp_f32_e32 v169, v87
	v_add_f32_e32 v237, v152, v237
	v_add_f32_e32 v238, v168, v238
	v_exp_f32_e32 v154, v104
	v_exp_f32_e32 v170, v88
	v_add_f32_e32 v237, v153, v237
	v_add_f32_e32 v238, v169, v238
	v_exp_f32_e32 v155, v105
	v_exp_f32_e32 v171, v89
	v_add_f32_e32 v237, v154, v237
	v_add_f32_e32 v238, v170, v238
	v_exp_f32_e32 v156, v106
	v_exp_f32_e32 v172, v90
	v_add_f32_e32 v237, v155, v237
	v_add_f32_e32 v238, v171, v238
	v_exp_f32_e32 v157, v107
	v_exp_f32_e32 v173, v91
	v_add_f32_e32 v237, v156, v237
	v_add_f32_e32 v238, v172, v238
	v_exp_f32_e32 v158, v108
	v_exp_f32_e32 v174, v92
	v_add_f32_e32 v237, v157, v237
	v_add_f32_e32 v238, v173, v238
	v_exp_f32_e32 v159, v109
	v_exp_f32_e32 v175, v93
	v_add_f32_e32 v237, v158, v237
	v_add_f32_e32 v238, v174, v238
	v_exp_f32_e32 v160, v110
	v_exp_f32_e32 v176, v94
	v_add_f32_e32 v237, v159, v237
	v_add_f32_e32 v238, v175, v238
	v_exp_f32_e32 v161, v111
	v_exp_f32_e32 v177, v95
	v_add_f32_e32 v237, v160, v237
	v_add_f32_e32 v238, v176, v238
	v_exp_f32_e32 v162, v112
	v_exp_f32_e32 v178, v96
	v_add_f32_e32 v237, v161, v237
	v_add_f32_e32 v238, v177, v238
	v_exp_f32_e32 v163, v113
	v_exp_f32_e32 v179, v97
	v_add_f32_e32 v237, v162, v237
	v_add_f32_e32 v238, v178, v238
	s_nop 0
	v_add_f32_e32 v237, v163, v237
	v_add_f32_e32 v238, v179, v238
	v_add_f32_e32 v204, v237, v238
	v_cmp_lt_f32_e32 vcc, s85, v204
	s_cbranch_vccnz .Ldb_s_slow
; __device__ __forceinline__ unsigned cvtpk(float lo, float hi) { f32x2 v = {lo, hi}; bf16x2_t b = __builtin_convertvector(v, bf16x2_t); return __builtin_bit_cast(unsigned, b); }
; template <bool DIFF>
; __device__ __forceinline__ void attn_unit(const AttnP& A, int b, int h, int qi, ldsp lds) {
;     ...
;             bf16x8 pw[4];
; #pragma unroll
;             for (int j = 0; j < 4; ++j) {
;                 u32x4 pk;
;                 if (j < 2) { const int rb = 8 * (j & 1); pk.x = cvtpk(s0[rb], s0[rb + 1]); pk.y = cvtpk(s0[rb + 2], s0[rb + 3]); pk.z = cvtpk(s0[rb + 4], s0[rb + 5]); pk.w = cvtpk(s0[rb + 6], s0[rb + 7]); }
;                 else { const int rb = 8 * (j & 1); pk.x = cvtpk(s1[rb], s1[rb + 1]); pk.y = cvtpk(s1[rb + 2], s1[rb + 3]); pk.z = cvtpk(s1[rb + 4], s1[rb + 5]); pk.w = cvtpk(s1[rb + 6], s1[rb + 7]); }
;                 pw[j] = __builtin_bit_cast(bf16x8, pk);
;             }
;             __builtin_amdgcn_sched_barrier(0);
;             __builtin_amdgcn_s_setprio(1);
; #pragma unroll
;             for (int t = 0; t < 2; ++t)
; #pragma unroll
;                 for (int j = 0; j < 4; ++j) {
;                     const bf16x8 vf = (bf16x8){vlo[t * 4 + j][0], vlo[t * 4 + j][1], vlo[t * 4 + j][2], vlo[t * 4 + j][3], vhi[t * 4 + j][0], vhi[t * 4 + j][1], vhi[t * 4 + j][2], vhi[t * 4 + j][3]};
;                     o[t] = __builtin_amdgcn_mfma_f32_32x32x16_bf16(vf, pw[j], o[t], 0, 0, 0);
;                 }
;             if (DIFF) {
; #pragma unroll
;                 for (int t = 2; t < NTD; ++t)
; #pragma unroll
;                     for (int j = 0; j < 4; ++j) { vlo[(t - 2) * 4 + j] = vtr(Vb + trb + (16 * j) * VP + t * 64); vhi[(t - 2) * 4 + j] = vtr(Vb + trb + (16 * j + 8) * VP + t * 64); }
;                 __builtin_amdgcn_sched_barrier(0);
; #pragma unroll
;                 for (int t = 2; t < NTD; ++t)
; #pragma unroll
;                     for (int j = 0; j < 4; ++j) {
;                         const int i = (t - 2) * 4 + j;
;                         const bf16x8 vf = (bf16x8){vlo[i][0], vlo[i][1], vlo[i][2], vlo[i][3], vhi[i][0], vhi[i][1], vhi[i][2], vhi[i][3]};
;                         o[t] = __builtin_amdgcn_mfma_f32_32x32x16_bf16(vf, pw[j], o[t], 0, 0, 0);
;                     }
;             }
;             __builtin_amdgcn_s_setprio(0);
;         }
;         if (kt + 1 < nt) STORE_TILE((kt + 1) & 1);
;         __syncthreads();
;     }
	ds_read_b64_tr_b16 v[90:91], v231 offset:17472
	ds_read_b64_tr_b16 v[92:93], v231 offset:20032
	ds_read_b64_tr_b16 v[94:95], v231 offset:17408
	ds_read_b64_tr_b16 v[96:97], v231 offset:19968
	ds_read_b64_tr_b16 v[106:107], v231 offset:22592
	ds_read_b64_tr_b16 v[108:109], v231 offset:25152
	ds_read_b64_tr_b16 v[110:111], v231 offset:22528
	ds_read_b64_tr_b16 v[112:113], v231 offset:25088
	ds_read_b64_tr_b16 v[240:241], v231 offset:27712
	ds_read_b64_tr_b16 v[242:243], v231 offset:30272
	v_cvt_pk_bf16_f32 v98, v148, v149
	v_cvt_pk_bf16_f32 v99, v150, v151
	v_cvt_pk_bf16_f32 v100, v152, v153
	v_cvt_pk_bf16_f32 v101, v154, v155
	v_cvt_pk_bf16_f32 v102, v156, v157
	v_cvt_pk_bf16_f32 v103, v158, v159
	v_cvt_pk_bf16_f32 v104, v160, v161
	v_cvt_pk_bf16_f32 v105, v162, v163
	v_cvt_pk_bf16_f32 v82, v164, v165
	v_cvt_pk_bf16_f32 v83, v166, v167
	v_cvt_pk_bf16_f32 v84, v168, v169
	v_cvt_pk_bf16_f32 v85, v170, v171
	v_cvt_pk_bf16_f32 v86, v172, v173
	v_cvt_pk_bf16_f32 v87, v174, v175
	v_cvt_pk_bf16_f32 v88, v176, v177
	v_cvt_pk_bf16_f32 v89, v178, v179
	v_add_f32_e32 v230, v204, v230
	ds_read_b64_tr_b16 v[148:149], v231 offset:27648
	ds_read_b64_tr_b16 v[150:151], v231 offset:30208
	ds_read_b64_tr_b16 v[152:153], v231 offset:32768
	ds_read_b64_tr_b16 v[154:155], v231 offset:35328
	ds_read_b64_tr_b16 v[156:157], v231 offset:32832
	ds_read_b64_tr_b16 v[158:159], v231 offset:35392
	s_setprio 1
	s_waitcnt lgkmcnt(14)
	v_mfma_f32_32x32x16_bf16 v[34:49], v[90:93], v[98:101], v[34:49]
	ds_read_b64_tr_b16 v[160:161], v231 offset:17536
	ds_read_b64_tr_b16 v[162:163], v231 offset:20096
	s_waitcnt lgkmcnt(14)
	v_mfma_f32_32x32x16_bf16 v[50:65], v[94:97], v[98:101], v[50:65]
	ds_read_b64_tr_b16 v[164:165], v231 offset:17600
	ds_read_b64_tr_b16 v[166:167], v231 offset:20160
	s_waitcnt lgkmcnt(14)
	v_mfma_f32_32x32x16_bf16 v[34:49], v[106:109], v[102:105], v[34:49]
	ds_read_b64_tr_b16 v[168:169], v231 offset:22656
	ds_read_b64_tr_b16 v[170:171], v231 offset:25216
	s_waitcnt lgkmcnt(14)
	v_mfma_f32_32x32x16_bf16 v[50:65], v[110:113], v[102:105], v[50:65]
	ds_read_b64_tr_b16 v[172:173], v231 offset:22720
	ds_read_b64_tr_b16 v[174:175], v231 offset:25280
	s_waitcnt lgkmcnt(14)
	v_mfma_f32_32x32x16_bf16 v[34:49], v[240:243], v[82:85], v[34:49]
	ds_read_b64_tr_b16 v[176:177], v231 offset:27776
	ds_read_b64_tr_b16 v[178:179], v231 offset:30336
	s_waitcnt lgkmcnt(14)
	v_mfma_f32_32x32x16_bf16 v[50:65], v[148:151], v[82:85], v[50:65]
	ds_read_b64_tr_b16 v[90:91], v231 offset:27840
	ds_read_b64_tr_b16 v[92:93], v231 offset:30400
	s_waitcnt lgkmcnt(14)
	v_mfma_f32_32x32x16_bf16 v[50:65], v[152:155], v[86:89], v[50:65]
	ds_read_b64_tr_b16 v[94:95], v231 offset:32896
	ds_read_b64_tr_b16 v[96:97], v231 offset:35456
	s_waitcnt lgkmcnt(14)
	v_mfma_f32_32x32x16_bf16 v[34:49], v[156:159], v[86:89], v[34:49]
	ds_read_b64_tr_b16 v[106:107], v231 offset:32960
	ds_read_b64_tr_b16 v[108:109], v231 offset:35520
	s_waitcnt lgkmcnt(14)
	v_mfma_f32_32x32x16_bf16 v[18:33], v[160:163], v[98:101], v[18:33]
	ds_read_b128 v[240:243], v234 offset:38144
	s_waitcnt lgkmcnt(13)
	v_mfma_f32_32x32x16_bf16 v[2:17], v[164:167], v[98:101], v[2:17]
	ds_read_b128 v[148:151], v234 offset:46848
	s_waitcnt lgkmcnt(12)
	v_mfma_f32_32x32x16_bf16 v[18:33], v[168:171], v[102:105], v[18:33]
	ds_read_b128 v[152:155], v234 offset:38176
	s_waitcnt lgkmcnt(11)
	v_mfma_f32_32x32x16_bf16 v[2:17], v[172:175], v[102:105], v[2:17]
	ds_read_b128 v[156:159], v234 offset:46880
	s_waitcnt lgkmcnt(10)
	v_mfma_f32_32x32x16_bf16 v[18:33], v[176:179], v[82:85], v[18:33]
	ds_read_b128 v[160:163], v234 offset:38208
	s_waitcnt lgkmcnt(9)
	v_mfma_f32_32x32x16_bf16 v[2:17], v[90:93], v[82:85], v[2:17]
	ds_read_b128 v[164:167], v234 offset:46912
	s_waitcnt lgkmcnt(8)
	v_mfma_f32_32x32x16_bf16 v[18:33], v[94:97], v[86:89], v[18:33]
	ds_read_b128 v[168:171], v234 offset:38240
	s_waitcnt lgkmcnt(7)
	v_mfma_f32_32x32x16_bf16 v[2:17], v[106:109], v[86:89], v[2:17]
	ds_read_b128 v[172:175], v234 offset:46944
	s_waitcnt lgkmcnt(7)
	v_mfma_f32_32x32x16_bf16 v[98:113], v[240:243], v[116:119], v[66:81]
	s_waitcnt vmcnt(0)
	ds_write_b128 v226, v[132:135]
	s_waitcnt lgkmcnt(7)
	v_mfma_f32_32x32x16_bf16 v[82:97], v[148:151], v[116:119], v[66:81]
	ds_write_b128 v228, v[140:143]
	s_waitcnt lgkmcnt(7)
	v_mfma_f32_32x32x16_bf16 v[98:113], v[152:155], v[120:123], v[98:113]
	ds_write_b128 v227, v[136:139] offset:55552
	s_waitcnt lgkmcnt(7)
	v_mfma_f32_32x32x16_bf16 v[82:97], v[156:159], v[120:123], v[82:97]
	ds_write_b128 v229, v[144:147] offset:55552
	s_waitcnt lgkmcnt(7)
	v_mfma_f32_32x32x16_bf16 v[98:113], v[160:163], v[124:127], v[98:113]
	global_load_dwordx4 v[136:139], v[196:197], off offset:2048
	global_load_dwordx4 v[144:147], v[198:199], off offset:2048
	v_lshl_add_u64 v[196:197], v[196:197], 0, s[26:27]
	s_waitcnt lgkmcnt(6)
	v_mfma_f32_32x32x16_bf16 v[82:97], v[164:167], v[124:127], v[82:97]
	v_lshl_add_u64 v[198:199], v[198:199], 0, s[26:27]
	global_load_dwordx4 v[132:135], v[196:197], off offset:1024
	global_load_dwordx4 v[140:143], v[198:199], off offset:1024
	s_waitcnt lgkmcnt(5)
	v_mfma_f32_32x32x16_bf16 v[98:113], v[168:171], v[128:131], v[98:113]
	s_waitcnt lgkmcnt(4)
	v_mfma_f32_32x32x16_bf16 v[82:97], v[172:175], v[128:131], v[82:97]
	s_setprio 0
	s_waitcnt lgkmcnt(0)
	s_barrier
	s_add_i32 s75, s75, 1
	s_add_i32 s74, s74, 64
	s_cmp_le_i32 s75, s23
	s_cbranch_scc1 .Ldb_s_even
